# v50 + down GEMM (K=2816) K-loop LDS-DMA staging rebalanced 6/2 -> 4/4 per super-phase as well
# speedup vs baseline: 1.0113x; 1.0023x over previous
; #define PG8_STAGE(bufoff, gbase, voff) do { _Pragma("unroll") for (int _i = 0; _i < 2; ++_i) \
;         __builtin_amdgcn_global_load_lds((const unsigned*)((const char*)(gbase) + (voff)[_i]), (PG8_LAS unsigned*)(lds + (bufoff) + ldsw + _i * 8192), 16, 0, 0); } while (0)
; #define PG8_WAIT_V(n) asm volatile("s_waitcnt vmcnt(" #n ")" ::: "memory")
; #define PG8_BAR __builtin_amdgcn_s_barrier()
; template <class Epi, class Sched, bool ALIGN_EPI = false, bool SP2 = false>
; __device__ __forceinline__ void gemm_phase(PG8_LAS unsigned char* lds, const Gemm g, const Sched& S, const Epi& E) {
;     ...
;     for (int i = 0; i < 2; ++i) { int R, C; stage_rc(tid * 16 + i * 8192, R, C); const int Rb = Epi::PERM ? ((R & ~31) + perm32(R & 31)) : R;
;         voffA[i] = (unsigned)(R * K + C) * 2u; voffB[i] = (unsigned)(Rb * K + C) * 2u; }
;     const size_t kstep = (size_t)(BK * 2);
;     const size_t hstep = (size_t)HALF * K * 2;
;     const size_t tstep = 2 * hstep;
;     const unsigned ldsw = (unsigned)wid * 1024u;
;     const int aoff = lds_byte(wr * 64 + fr, fq * 8), boff = lds_byte(wc * 32 + fr, fq * 8);
;     ...
;         PG8_STAGE(PG8_SB(0, 0), cB, voffB); PG8_STAGE(PG8_SB(0, 1), cB + hstep, voffB); PG8_STAGE(PG8_SA(0, 0), cA, voffA); PG8_STAGE(PG8_SA(0, 1), cA + hstep, voffA);
;         if (wr == 1) PG8_BAR;
;         PG8_WAIT_V(2); PG8_BAR;
;         PG8_STAGE(PG8_SB(1, 0), cB + kstep, voffB); PG8_STAGE(PG8_SA(1, 0), cA + kstep, voffA); PG8_STAGE(PG8_SB(1, 1), cB + hstep + kstep, voffB);
;         PG8_WAIT_V(6); PG8_BAR;
; __global__ void __launch_bounds__(NTHR, 2) fwd_megakernel(Args a) {
;     ...
;                 for (int rep = 0; rep < RPT_DOWN; ++rep) { pg8::EpiRes E{XB, XL, part, (ph == NPHASES - 1 && rep == RPT_DOWN - 1) ? outp : nullptr, rep == RPT_DOWN - 1 ? 0.5f : 0.0f};
.LBB0_250:
	s_cmp_eq_u32 s80, 28
	s_cselect_b32 s47, s77, 0
	s_cselect_b32 s46, s76, 0
	v_bfe_u32 v13, v12, 4, 2
	s_cmp_eq_u64 s[46:47], 0
	v_and_b32_e32 v12, 15, v12
	v_lshlrev_b32_e32 v19, 4, v13
	v_readlane_b32 s14, v254, 23
	s_cselect_b64 s[48:49], -1, 0
	s_cmp_lg_u64 s[46:47], 0
	v_lshl_or_b32 v158, s7, 6, v12
	v_lshl_or_b32 v19, v12, 6, v19
	v_lshlrev_b32_e32 v12, 2, v12
	v_mov_b32_e32 v175, v157
	v_readlane_b32 s15, v254, 24
	s_cselect_b64 s[50:51], -1, 0
	s_and_b32 s10, s8, 3
	s_lshl_b32 s7, s7, 13
	v_and_b32_e32 v20, 32, v12
	s_add_i32 m0, s21, 0x18000
	v_lshl_add_u64 v[0:1], v[0:1], 0, s[96:97]
	v_lshl_add_u64 v[14:15], s[14:15], 0, v[174:175]
	v_mov_b32_e32 v173, v157
	v_bitop3_b32 v21, v19, s7, v20 bitop3:0xde
	s_lshl_b32 s7, s10, 12
	s_waitcnt vmcnt(2)
	s_barrier
	global_load_lds_dwordx4 v[0:1], off
	v_lshl_add_u64 v[0:1], v[2:3], 0, s[96:97]
	s_add_i32 m0, s21, 0x1a000
	s_add_i32 s57, s21, 0x8000
	s_add_i32 s58, s21, 0xa000
	v_lshl_add_u64 v[16:17], s[14:15], 0, v[172:173]
	global_load_lds_dwordx4 v[0:1], off
	s_add_u32 s8, s12, 0xb0080
	s_addc_u32 s9, s13, 0
	s_add_i32 m0, s21, 0x1c000
	v_lshl_add_u64 v[0:1], s[8:9], 0, v[156:157]
	global_load_lds_dwordx4 v[0:1], off
	v_lshl_add_u64 v[0:1], s[8:9], 0, v[170:171]
	s_add_i32 m0, s21, 0x1e000
	s_cmpk_lt_u32 s6, 0x100
	global_load_lds_dwordx4 v[0:1], off
	v_lshlrev_b32_e32 v0, 6, v13
	s_movk_i32 s6, 0x80
	s_movk_i32 s8, 0xb00
	s_cselect_b64 s[52:53], -1, 0
	v_bitop3_b32 v237, v0, 64, v12 bitop3:0x36
	v_bitop3_b32 v238, v0, s6, v12 bitop3:0x36
	s_lshl_b32 s6, s10, 2
	v_lshrrev_b32_e32 v1, 1, v9
	v_mul_lo_u32 v0, v8, s8
	s_mov_b32 s9, 0xb000
	v_bitop3_b32 v169, v19, s7, v20 bitop3:0xde
	s_add_u32 s59, s68, s6
	v_mad_u64_u32 v[0:1], s[6:7], v1, s9, v[0:1]
	v_lshlrev_b32_e32 v18, 3, v13
	v_or_b32_e32 v0, v0, v10
	v_lshl_or_b32 v236, s10, 5, v18
	v_add_lshl_u32 v0, v0, v11, 1
	v_mov_b32_e32 v1, v157
	s_mov_b64 s[10:11], 0xb0080
	v_lshl_add_u64 v[176:177], v[0:1], 0, s[10:11]
	v_lshrrev_b32_e32 v1, 1, v4
	v_mul_lo_u32 v0, v5, s8
	v_mad_u64_u32 v[0:1], s[6:7], v1, s9, v[0:1]
	s_waitcnt vmcnt(4)
	v_or_b32_e32 v0, v0, v6
	v_add_lshl_u32 v0, v0, v7, 1
	v_mov_b32_e32 v1, v157
	v_readlane_b32 s6, v254, 21
	s_mov_b32 s56, 0
	v_cmp_eq_u32_e64 s[40:41], 0, v13
	s_addc_u32 s60, s69, 0
	v_lshl_add_u64 v[178:179], v[0:1], 0, s[10:11]
	v_add_u32_e32 v239, 0, v21
	v_readlane_b32 s61, v254, 6
	s_mov_b32 s28, s6
	s_mov_b64 s[10:11], s[14:15]
	s_barrier
	v_readlane_b32 s7, v254, 22
	s_branch .LBB0_253

; #define PG8_STAGE(bufoff, gbase, voff) do { _Pragma("unroll") for (int _i = 0; _i < 2; ++_i) \
;         __builtin_amdgcn_global_load_lds((const unsigned*)((const char*)(gbase) + (voff)[_i]), (PG8_LAS unsigned*)(lds + (bufoff) + ldsw + _i * 8192), 16, 0, 0); } while (0)
; #define PG8_LDA(dst, b, h) do { _Pragma("unroll") for (int m = 0; m < 4; ++m) _Pragma("unroll") for (int k = 0; k < 2; ++k) dst[m][k] = *(const PG8_LAS bf16x8*)(lds + PG8_SA(b, h) + aoff + m * 2048 + k * 1024); } while (0)
; #define PG8_LDB(dst, b, h) do { _Pragma("unroll") for (int n = 0; n < 2; ++n) _Pragma("unroll") for (int k = 0; k < 2; ++k) dst[n][k] = *(const PG8_LAS bf16x8*)(lds + PG8_SB(b, h) + boff + n * 2048 + k * 1024); } while (0)
; #define PG8_MMA(ai, bj, At, Bt) do { __builtin_amdgcn_s_setprio(1); _Pragma("unroll") for (int m = 0; m < 4; ++m) _Pragma("unroll") for (int n = 0; n < 2; ++n) _Pragma("unroll") for (int k = 0; k < 2; ++k) \
;         acc[ai][bj][m][n] = __builtin_amdgcn_mfma_f32_16x16x32_bf16(Bt[n][k], At[m][k], acc[ai][bj][m][n], 0, 0, 0); __builtin_amdgcn_s_setprio(0); } while (0)
; #define PG8_WAIT_V(n) asm volatile("s_waitcnt vmcnt(" #n ")" ::: "memory")
; #define PG8_WAIT_L(n) asm volatile("s_waitcnt lgkmcnt(" #n ")" ::: "memory")
; #define PG8_BAR __builtin_amdgcn_s_barrier()
; #define PG8_SCHED __builtin_amdgcn_sched_barrier(0)
; template <class Epi, class Sched, bool ALIGN_EPI = false, bool SP2 = false>
; __device__ __forceinline__ void gemm_phase(PG8_LAS unsigned char* lds, const Gemm g, const Sched& S, const Epi& E) {
;     ...
;             const char* a1 = cA + (size_t)(t + 1) * kstep;
;             const char* a2 = last ? nA : cA + (size_t)(t + 2) * kstep; const char* b2 = last ? nB : cB + (size_t)(t + 2) * kstep;
;             const char* a3 = a2 + kstep; const char* b3 = b2 + kstep;
;             if (last && has_next) S.a_ready(nxt);
;             if constexpr (SP2) {
;             PG8_LDB(B0, 0, 0); PG8_LDB(B1, 0, 1); PG8_SCHED; PG8_LDA(At, 0, 0); PG8_STAGE(PG8_SA(1, 1), a1 + hstep, voffA);
;             PG8_WAIT_V(8); PG8_WAIT_L(0); PG8_BAR; PG8_MMA(0, 0, At, B0); PG8_MMA(0, 1, At, B1); PG8_BAR; PG8_SCHED;
;             PG8_LDA(At, 0, 1); PG8_STAGE(PG8_SB(0, 0), b2, voffB); PG8_STAGE(PG8_SB(0, 1), b2 + hstep, voffB); PG8_STAGE(PG8_SA(0, 0), a2, voffA);
.LBB0_264:
	s_add_u32 s12, s10, 0x100
	s_addc_u32 s13, s11, 0
	s_add_i32 s34, 0, 0x10000
	s_cmp_eq_u32 s31, 40
	s_cselect_b32 s17, s7, s13
	s_cselect_b32 s16, s6, s12
	s_cselect_b32 s15, s9, s30
	s_cselect_b32 s14, s8, s29
	s_add_i32 s35, 0, 0x14000
	v_add_u32_e32 v132, s34, v169
	v_add_u32_e32 v180, s35, v169
	ds_read_b128 v[104:107], v132
	ds_read_b128 v[120:123], v132 offset:1024
	ds_read_b128 v[128:131], v132 offset:2048
	ds_read_b128 v[132:135], v132 offset:3072
	ds_read_b128 v[136:139], v180
	ds_read_b128 v[148:151], v180 offset:1024
	ds_read_b128 v[152:155], v180 offset:2048
	ds_read_b128 v[180:183], v180 offset:3072
	v_lshl_add_u64 v[220:221], s[10:11], 0, v[174:175]
	v_lshl_add_u64 v[222:223], s[10:11], 0, v[172:173]
	v_lshl_add_u64 v[220:221], v[220:221], 0, s[96:97]
	v_lshl_add_u64 v[222:223], v[222:223], 0, s[96:97]
	v_lshl_add_u64 v[216:217], s[10:11], 0, v[176:177]
	s_mov_b32 m0, s57
	ds_read_b128 v[184:187], v239
	ds_read_b128 v[188:191], v239 offset:1024
	ds_read_b128 v[192:195], v239 offset:2048
	ds_read_b128 v[196:199], v239 offset:3072
	ds_read_b128 v[200:203], v239 offset:4096
	ds_read_b128 v[204:207], v239 offset:5120
	ds_read_b128 v[208:211], v239 offset:6144
	ds_read_b128 v[212:215], v239 offset:7168
	global_load_lds_dwordx4 v[220:221], off
	s_mov_b32 m0, s58
	s_nop 0
	global_load_lds_dwordx4 v[222:223], off
	s_add_i32 m0, s21, 0xc000
	s_nop 0
	global_load_lds_dwordx4 v[216:217], off
	v_lshl_add_u64 v[216:217], s[10:11], 0, v[178:179]
	s_add_i32 m0, s21, 0xe000
	s_nop 0
	global_load_lds_dwordx4 v[216:217], off
	s_waitcnt vmcnt(8)
	s_waitcnt lgkmcnt(0)
	s_barrier
	s_waitcnt lgkmcnt(0)
	v_mfma_f32_16x16x32_bf16 v[144:147], v[104:107], v[184:187], v[144:147]
	v_mfma_f32_16x16x32_bf16 v[140:143], v[128:131], v[184:187], v[140:143]
	v_mfma_f32_16x16x32_bf16 v[112:115], v[104:107], v[192:195], v[112:115]
	v_mfma_f32_16x16x32_bf16 v[108:111], v[128:131], v[192:195], v[108:111]
	v_mfma_f32_16x16x32_bf16 v[92:95], v[104:107], v[200:203], v[92:95]
	v_mfma_f32_16x16x32_bf16 v[88:91], v[128:131], v[200:203], v[88:91]
	v_mfma_f32_16x16x32_bf16 v[76:79], v[104:107], v[208:211], v[76:79]
	v_mfma_f32_16x16x32_bf16 v[72:75], v[128:131], v[208:211], v[72:75]
	v_mfma_f32_16x16x32_bf16 v[144:147], v[120:123], v[188:191], v[144:147]
	v_mfma_f32_16x16x32_bf16 v[140:143], v[132:135], v[188:191], v[140:143]
	v_mfma_f32_16x16x32_bf16 v[112:115], v[120:123], v[196:199], v[112:115]
	v_mfma_f32_16x16x32_bf16 v[108:111], v[132:135], v[196:199], v[108:111]
	v_mfma_f32_16x16x32_bf16 v[92:95], v[120:123], v[204:207], v[92:95]
	v_mfma_f32_16x16x32_bf16 v[88:91], v[132:135], v[204:207], v[88:91]
	v_mfma_f32_16x16x32_bf16 v[76:79], v[120:123], v[212:215], v[76:79]
	v_mfma_f32_16x16x32_bf16 v[72:75], v[132:135], v[212:215], v[72:75]
	v_mfma_f32_16x16x32_bf16 v[124:127], v[136:139], v[184:187], v[124:127]
	v_mfma_f32_16x16x32_bf16 v[116:119], v[152:155], v[184:187], v[116:119]
	v_mfma_f32_16x16x32_bf16 v[100:103], v[136:139], v[192:195], v[100:103]
	v_mfma_f32_16x16x32_bf16 v[96:99], v[152:155], v[192:195], v[96:99]
	v_mfma_f32_16x16x32_bf16 v[84:87], v[136:139], v[200:203], v[84:87]
	v_mfma_f32_16x16x32_bf16 v[80:83], v[152:155], v[200:203], v[80:83]
	v_mfma_f32_16x16x32_bf16 v[68:71], v[136:139], v[208:211], v[68:71]
	v_mfma_f32_16x16x32_bf16 v[64:67], v[152:155], v[208:211], v[64:67]
	v_mfma_f32_16x16x32_bf16 v[124:127], v[148:151], v[188:191], v[124:127]
	v_mfma_f32_16x16x32_bf16 v[116:119], v[180:183], v[188:191], v[116:119]
	v_mfma_f32_16x16x32_bf16 v[100:103], v[148:151], v[196:199], v[100:103]
	v_mfma_f32_16x16x32_bf16 v[96:99], v[180:183], v[196:199], v[96:99]
	v_mfma_f32_16x16x32_bf16 v[84:87], v[148:151], v[204:207], v[84:87]
	v_mfma_f32_16x16x32_bf16 v[80:83], v[180:183], v[204:207], v[80:83]
	v_mfma_f32_16x16x32_bf16 v[68:71], v[148:151], v[212:215], v[68:71]
	v_mfma_f32_16x16x32_bf16 v[64:67], v[180:183], v[212:215], v[64:67]
	s_barrier
	s_add_i32 s10, s34, s20
	v_lshl_add_u64 v[216:217], s[14:15], 0, v[156:157]
	s_mov_b32 m0, s10
	ds_read_b128 v[184:187], v239 offset:16384
	ds_read_b128 v[188:191], v239 offset:17408
	ds_read_b128 v[192:195], v239 offset:18432
	ds_read_b128 v[196:199], v239 offset:19456
	ds_read_b128 v[200:203], v239 offset:20480
	ds_read_b128 v[204:207], v239 offset:21504
	ds_read_b128 v[208:211], v239 offset:22528
	ds_read_b128 v[212:215], v239 offset:23552
	global_load_lds_dwordx4 v[216:217], off
	s_add_i32 m0, s10, 0x2000
	s_add_u32 s10, s14, 0xb0000
	v_lshl_add_u64 v[218:219], s[14:15], 0, v[170:171]
	s_addc_u32 s11, s15, 0
	s_add_i32 s34, s35, s20
	global_load_lds_dwordx4 v[218:219], off
	v_lshl_add_u64 v[220:221], s[10:11], 0, v[156:157]
	s_mov_b32 m0, s34
	s_nop 0
	global_load_lds_dwordx4 v[220:221], off
	v_lshl_add_u64 v[220:221], s[10:11], 0, v[170:171]
	s_add_i32 m0, s34, 0x2000
	s_nop 0
	global_load_lds_dwordx4 v[220:221], off
	s_waitcnt vmcnt(6)
	s_waitcnt lgkmcnt(0)
	s_barrier
; #define PG8_STAGE(bufoff, gbase, voff) do { _Pragma("unroll") for (int _i = 0; _i < 2; ++_i) \
;         __builtin_amdgcn_global_load_lds((const unsigned*)((const char*)(gbase) + (voff)[_i]), (PG8_LAS unsigned*)(lds + (bufoff) + ldsw + _i * 8192), 16, 0, 0); } while (0)
; #define PG8_LDA(dst, b, h) do { _Pragma("unroll") for (int m = 0; m < 4; ++m) _Pragma("unroll") for (int k = 0; k < 2; ++k) dst[m][k] = *(const PG8_LAS bf16x8*)(lds + PG8_SA(b, h) + aoff + m * 2048 + k * 1024); } while (0)
; #define PG8_LDB(dst, b, h) do { _Pragma("unroll") for (int n = 0; n < 2; ++n) _Pragma("unroll") for (int k = 0; k < 2; ++k) dst[n][k] = *(const PG8_LAS bf16x8*)(lds + PG8_SB(b, h) + boff + n * 2048 + k * 1024); } while (0)
; #define PG8_MMA(ai, bj, At, Bt) do { __builtin_amdgcn_s_setprio(1); _Pragma("unroll") for (int m = 0; m < 4; ++m) _Pragma("unroll") for (int n = 0; n < 2; ++n) _Pragma("unroll") for (int k = 0; k < 2; ++k) \
;         acc[ai][bj][m][n] = __builtin_amdgcn_mfma_f32_16x16x32_bf16(Bt[n][k], At[m][k], acc[ai][bj][m][n], 0, 0, 0); __builtin_amdgcn_s_setprio(0); } while (0)
; #define PG8_WAIT_V(n) asm volatile("s_waitcnt vmcnt(" #n ")" ::: "memory")
; #define PG8_WAIT_L(n) asm volatile("s_waitcnt lgkmcnt(" #n ")" ::: "memory")
; #define PG8_BAR __builtin_amdgcn_s_barrier()
; #define PG8_SCHED __builtin_amdgcn_sched_barrier(0)
; template <class Epi, class Sched, bool ALIGN_EPI = false, bool SP2 = false>
; __device__ __forceinline__ void gemm_phase(PG8_LAS unsigned char* lds, const Gemm g, const Sched& S, const Epi& E) {
;     ...
;             PG8_WAIT_V(8); PG8_WAIT_L(0); PG8_BAR; PG8_MMA(1, 0, At, B0); PG8_MMA(1, 1, At, B1); PG8_BAR; PG8_SCHED;
;             PG8_LDB(B0, 1, 0); PG8_LDB(B1, 1, 1); PG8_SCHED; PG8_LDA(At, 1, 0); PG8_STAGE(PG8_SA(0, 1), a2 + hstep, voffA);
	s_waitcnt lgkmcnt(0)
	v_mfma_f32_16x16x32_bf16 v[60:63], v[104:107], v[184:187], v[60:63]
	v_mfma_f32_16x16x32_bf16 v[56:59], v[128:131], v[184:187], v[56:59]
	v_mfma_f32_16x16x32_bf16 v[44:47], v[104:107], v[192:195], v[44:47]
	v_mfma_f32_16x16x32_bf16 v[40:43], v[128:131], v[192:195], v[40:43]
	v_mfma_f32_16x16x32_bf16 v[28:31], v[104:107], v[200:203], v[28:31]
	v_mfma_f32_16x16x32_bf16 v[24:27], v[128:131], v[200:203], v[24:27]
	v_mfma_f32_16x16x32_bf16 v[12:15], v[104:107], v[208:211], v[12:15]
	v_mfma_f32_16x16x32_bf16 v[8:11], v[128:131], v[208:211], v[8:11]
	v_mfma_f32_16x16x32_bf16 v[60:63], v[120:123], v[188:191], v[60:63]
	v_mfma_f32_16x16x32_bf16 v[56:59], v[132:135], v[188:191], v[56:59]
	v_mfma_f32_16x16x32_bf16 v[44:47], v[120:123], v[196:199], v[44:47]
	v_mfma_f32_16x16x32_bf16 v[40:43], v[132:135], v[196:199], v[40:43]
	v_mfma_f32_16x16x32_bf16 v[28:31], v[120:123], v[204:207], v[28:31]
	v_mfma_f32_16x16x32_bf16 v[24:27], v[132:135], v[204:207], v[24:27]
	v_mfma_f32_16x16x32_bf16 v[12:15], v[120:123], v[212:215], v[12:15]
	v_mfma_f32_16x16x32_bf16 v[8:11], v[132:135], v[212:215], v[8:11]
	v_mfma_f32_16x16x32_bf16 v[52:55], v[136:139], v[184:187], v[52:55]
	v_mfma_f32_16x16x32_bf16 v[48:51], v[152:155], v[184:187], v[48:51]
	v_mfma_f32_16x16x32_bf16 v[36:39], v[136:139], v[192:195], v[36:39]
	v_mfma_f32_16x16x32_bf16 v[32:35], v[152:155], v[192:195], v[32:35]
	v_mfma_f32_16x16x32_bf16 v[20:23], v[136:139], v[200:203], v[20:23]
	v_mfma_f32_16x16x32_bf16 v[16:19], v[152:155], v[200:203], v[16:19]
	v_mfma_f32_16x16x32_bf16 v[4:7], v[136:139], v[208:211], v[4:7]
	v_mfma_f32_16x16x32_bf16 v[0:3], v[152:155], v[208:211], v[0:3]
	v_mfma_f32_16x16x32_bf16 v[52:55], v[148:151], v[188:191], v[52:55]
	v_mfma_f32_16x16x32_bf16 v[48:51], v[180:183], v[188:191], v[48:51]
	v_mfma_f32_16x16x32_bf16 v[36:39], v[148:151], v[196:199], v[36:39]
	v_mfma_f32_16x16x32_bf16 v[32:35], v[180:183], v[196:199], v[32:35]
	v_mfma_f32_16x16x32_bf16 v[20:23], v[148:151], v[204:207], v[20:23]
	v_mfma_f32_16x16x32_bf16 v[16:19], v[180:183], v[204:207], v[16:19]
	v_mfma_f32_16x16x32_bf16 v[4:7], v[148:151], v[212:215], v[4:7]
	v_mfma_f32_16x16x32_bf16 v[0:3], v[180:183], v[212:215], v[0:3]
	s_barrier
	s_add_i32 s34, 0, 0x18000
	s_add_i32 s35, 0, 0x1c000
	v_add_u32_e32 v132, s34, v169
	v_add_u32_e32 v180, s35, v169
	ds_read_b128 v[104:107], v132
	ds_read_b128 v[120:123], v132 offset:1024
	ds_read_b128 v[128:131], v132 offset:2048
	ds_read_b128 v[132:135], v132 offset:3072
	ds_read_b128 v[136:139], v180
	ds_read_b128 v[148:151], v180 offset:1024
	ds_read_b128 v[152:155], v180 offset:2048
	ds_read_b128 v[180:183], v180 offset:3072
	v_lshl_add_u64 v[220:221], s[16:17], 0, v[174:175]
	v_lshl_add_u64 v[222:223], s[16:17], 0, v[172:173]
	s_add_u32 s10, s16, 0xb0000
	s_addc_u32 s11, s17, 0
	s_mov_b32 m0, s21
	v_lshl_add_u64 v[224:225], s[10:11], 0, v[174:175]
	ds_read_b128 v[184:187], v239 offset:32768
	ds_read_b128 v[188:191], v239 offset:33792
	ds_read_b128 v[192:195], v239 offset:34816
	ds_read_b128 v[196:199], v239 offset:35840
	ds_read_b128 v[200:203], v239 offset:36864
	ds_read_b128 v[204:207], v239 offset:37888
	ds_read_b128 v[208:211], v239 offset:38912
	ds_read_b128 v[212:215], v239 offset:39936
	global_load_lds_dwordx4 v[220:221], off
	s_mov_b32 m0, s27
	s_nop 0
	global_load_lds_dwordx4 v[222:223], off
	s_mov_b32 m0, s54
	s_nop 0
	global_load_lds_dwordx4 v[224:225], off
	v_lshl_add_u64 v[224:225], s[10:11], 0, v[172:173]
	s_mov_b32 m0, s55
	s_nop 0
	global_load_lds_dwordx4 v[224:225], off
	s_waitcnt vmcnt(8)
	s_waitcnt lgkmcnt(0)
	s_barrier
; #define PG8_STAGE(bufoff, gbase, voff) do { _Pragma("unroll") for (int _i = 0; _i < 2; ++_i) \
;         __builtin_amdgcn_global_load_lds((const unsigned*)((const char*)(gbase) + (voff)[_i]), (PG8_LAS unsigned*)(lds + (bufoff) + ldsw + _i * 8192), 16, 0, 0); } while (0)
; #define PG8_LDA(dst, b, h) do { _Pragma("unroll") for (int m = 0; m < 4; ++m) _Pragma("unroll") for (int k = 0; k < 2; ++k) dst[m][k] = *(const PG8_LAS bf16x8*)(lds + PG8_SA(b, h) + aoff + m * 2048 + k * 1024); } while (0)
; #define PG8_MMA(ai, bj, At, Bt) do { __builtin_amdgcn_s_setprio(1); _Pragma("unroll") for (int m = 0; m < 4; ++m) _Pragma("unroll") for (int n = 0; n < 2; ++n) _Pragma("unroll") for (int k = 0; k < 2; ++k) \
;         acc[ai][bj][m][n] = __builtin_amdgcn_mfma_f32_16x16x32_bf16(Bt[n][k], At[m][k], acc[ai][bj][m][n], 0, 0, 0); __builtin_amdgcn_s_setprio(0); } while (0)
; #define PG8_WAIT_V(n) asm volatile("s_waitcnt vmcnt(" #n ")" ::: "memory")
; #define PG8_WAIT_L(n) asm volatile("s_waitcnt lgkmcnt(" #n ")" ::: "memory")
; #define PG8_BAR __builtin_amdgcn_s_barrier()
; #define PG8_SCHED __builtin_amdgcn_sched_barrier(0)
; template <class Epi, class Sched, bool ALIGN_EPI = false, bool SP2 = false>
; __device__ __forceinline__ void gemm_phase(PG8_LAS unsigned char* lds, const Gemm g, const Sched& S, const Epi& E) {
;     ...
;         for (int t = 0; t < nt; t += 2) {
;     ...
;             PG8_WAIT_V(8); PG8_WAIT_L(0); PG8_BAR; PG8_MMA(0, 0, At, B0); PG8_MMA(0, 1, At, B1); PG8_BAR; PG8_SCHED;
;             PG8_LDA(At, 1, 1); PG8_STAGE(PG8_SB(1, 0), b3, voffB); PG8_STAGE(PG8_SB(1, 1), b3 + hstep, voffB); PG8_STAGE(PG8_SA(1, 0), a3, voffA);
;             PG8_WAIT_V(8); PG8_WAIT_L(0); PG8_BAR; PG8_MMA(1, 0, At, B0); PG8_MMA(1, 1, At, B1); PG8_BAR; PG8_SCHED;
	s_waitcnt lgkmcnt(0)
	v_mfma_f32_16x16x32_bf16 v[144:147], v[104:107], v[184:187], v[144:147]
	v_mfma_f32_16x16x32_bf16 v[140:143], v[128:131], v[184:187], v[140:143]
	v_mfma_f32_16x16x32_bf16 v[112:115], v[104:107], v[192:195], v[112:115]
	v_mfma_f32_16x16x32_bf16 v[108:111], v[128:131], v[192:195], v[108:111]
	v_mfma_f32_16x16x32_bf16 v[92:95], v[104:107], v[200:203], v[92:95]
	v_mfma_f32_16x16x32_bf16 v[88:91], v[128:131], v[200:203], v[88:91]
	v_mfma_f32_16x16x32_bf16 v[76:79], v[104:107], v[208:211], v[76:79]
	v_mfma_f32_16x16x32_bf16 v[72:75], v[128:131], v[208:211], v[72:75]
	v_mfma_f32_16x16x32_bf16 v[144:147], v[120:123], v[188:191], v[144:147]
	v_mfma_f32_16x16x32_bf16 v[140:143], v[132:135], v[188:191], v[140:143]
	v_mfma_f32_16x16x32_bf16 v[112:115], v[120:123], v[196:199], v[112:115]
	v_mfma_f32_16x16x32_bf16 v[108:111], v[132:135], v[196:199], v[108:111]
	v_mfma_f32_16x16x32_bf16 v[92:95], v[120:123], v[204:207], v[92:95]
	v_mfma_f32_16x16x32_bf16 v[88:91], v[132:135], v[204:207], v[88:91]
	v_mfma_f32_16x16x32_bf16 v[76:79], v[120:123], v[212:215], v[76:79]
	v_mfma_f32_16x16x32_bf16 v[72:75], v[132:135], v[212:215], v[72:75]
	v_mfma_f32_16x16x32_bf16 v[124:127], v[136:139], v[184:187], v[124:127]
	v_mfma_f32_16x16x32_bf16 v[116:119], v[152:155], v[184:187], v[116:119]
	v_mfma_f32_16x16x32_bf16 v[100:103], v[136:139], v[192:195], v[100:103]
	v_mfma_f32_16x16x32_bf16 v[96:99], v[152:155], v[192:195], v[96:99]
	v_mfma_f32_16x16x32_bf16 v[84:87], v[136:139], v[200:203], v[84:87]
	v_mfma_f32_16x16x32_bf16 v[80:83], v[152:155], v[200:203], v[80:83]
	v_mfma_f32_16x16x32_bf16 v[68:71], v[136:139], v[208:211], v[68:71]
	v_mfma_f32_16x16x32_bf16 v[64:67], v[152:155], v[208:211], v[64:67]
	v_mfma_f32_16x16x32_bf16 v[124:127], v[148:151], v[188:191], v[124:127]
	v_mfma_f32_16x16x32_bf16 v[116:119], v[180:183], v[188:191], v[116:119]
	v_mfma_f32_16x16x32_bf16 v[100:103], v[148:151], v[196:199], v[100:103]
	v_mfma_f32_16x16x32_bf16 v[96:99], v[180:183], v[196:199], v[96:99]
	v_mfma_f32_16x16x32_bf16 v[84:87], v[148:151], v[204:207], v[84:87]
	v_mfma_f32_16x16x32_bf16 v[80:83], v[180:183], v[204:207], v[80:83]
	v_mfma_f32_16x16x32_bf16 v[68:71], v[148:151], v[212:215], v[68:71]
	v_mfma_f32_16x16x32_bf16 v[64:67], v[180:183], v[212:215], v[64:67]
	s_barrier
	s_add_i32 s10, s34, s20
	v_lshl_add_u64 v[216:217], v[216:217], 0, s[96:97]
	s_mov_b32 m0, s10
	ds_read_b128 v[184:187], v239 offset:49152
	ds_read_b128 v[188:191], v239 offset:50176
	ds_read_b128 v[192:195], v239 offset:51200
	ds_read_b128 v[196:199], v239 offset:52224
	ds_read_b128 v[200:203], v239 offset:53248
	ds_read_b128 v[204:207], v239 offset:54272
	ds_read_b128 v[208:211], v239 offset:55296
	ds_read_b128 v[212:215], v239 offset:56320
	global_load_lds_dwordx4 v[216:217], off
	s_add_i32 m0, s10, 0x2000
	s_add_u32 s10, s14, 0xb0080
	v_lshl_add_u64 v[216:217], v[218:219], 0, s[96:97]
	s_addc_u32 s11, s15, 0
	s_add_i32 s14, s35, s20
	global_load_lds_dwordx4 v[216:217], off
	v_lshl_add_u64 v[216:217], s[10:11], 0, v[156:157]
	s_mov_b32 m0, s14
	s_nop 0
	global_load_lds_dwordx4 v[216:217], off
	v_lshl_add_u64 v[216:217], s[10:11], 0, v[170:171]
	s_add_i32 m0, s14, 0x2000
	s_nop 0
	global_load_lds_dwordx4 v[216:217], off
	s_waitcnt vmcnt(6)
	s_waitcnt lgkmcnt(0)
	s_barrier
	s_waitcnt lgkmcnt(0)
	v_mfma_f32_16x16x32_bf16 v[60:63], v[104:107], v[184:187], v[60:63]
	v_mfma_f32_16x16x32_bf16 v[56:59], v[128:131], v[184:187], v[56:59]
	v_mfma_f32_16x16x32_bf16 v[44:47], v[104:107], v[192:195], v[44:47]
	v_mfma_f32_16x16x32_bf16 v[40:43], v[128:131], v[192:195], v[40:43]
	v_mfma_f32_16x16x32_bf16 v[28:31], v[104:107], v[200:203], v[28:31]
	v_mfma_f32_16x16x32_bf16 v[24:27], v[128:131], v[200:203], v[24:27]
	v_mfma_f32_16x16x32_bf16 v[12:15], v[104:107], v[208:211], v[12:15]
	v_mfma_f32_16x16x32_bf16 v[8:11], v[128:131], v[208:211], v[8:11]
	v_mfma_f32_16x16x32_bf16 v[60:63], v[120:123], v[188:191], v[60:63]
	v_mfma_f32_16x16x32_bf16 v[56:59], v[132:135], v[188:191], v[56:59]
	v_mfma_f32_16x16x32_bf16 v[44:47], v[120:123], v[196:199], v[44:47]
	v_mfma_f32_16x16x32_bf16 v[40:43], v[132:135], v[196:199], v[40:43]
	v_mfma_f32_16x16x32_bf16 v[28:31], v[120:123], v[204:207], v[28:31]
	v_mfma_f32_16x16x32_bf16 v[24:27], v[132:135], v[204:207], v[24:27]
	v_mfma_f32_16x16x32_bf16 v[12:15], v[120:123], v[212:215], v[12:15]
	v_mfma_f32_16x16x32_bf16 v[8:11], v[132:135], v[212:215], v[8:11]
	v_mfma_f32_16x16x32_bf16 v[52:55], v[136:139], v[184:187], v[52:55]
	v_mfma_f32_16x16x32_bf16 v[48:51], v[152:155], v[184:187], v[48:51]
	v_mfma_f32_16x16x32_bf16 v[36:39], v[136:139], v[192:195], v[36:39]
	v_mfma_f32_16x16x32_bf16 v[32:35], v[152:155], v[192:195], v[32:35]
	v_mfma_f32_16x16x32_bf16 v[20:23], v[136:139], v[200:203], v[20:23]
	v_mfma_f32_16x16x32_bf16 v[16:19], v[152:155], v[200:203], v[16:19]
	v_mfma_f32_16x16x32_bf16 v[4:7], v[136:139], v[208:211], v[4:7]
	v_mfma_f32_16x16x32_bf16 v[0:3], v[152:155], v[208:211], v[0:3]
	v_mfma_f32_16x16x32_bf16 v[52:55], v[148:151], v[188:191], v[52:55]
	v_mfma_f32_16x16x32_bf16 v[48:51], v[180:183], v[188:191], v[48:51]
	v_mfma_f32_16x16x32_bf16 v[36:39], v[148:151], v[196:199], v[36:39]
	v_mfma_f32_16x16x32_bf16 v[32:35], v[180:183], v[196:199], v[32:35]
	v_mfma_f32_16x16x32_bf16 v[20:23], v[148:151], v[204:207], v[20:23]
	v_mfma_f32_16x16x32_bf16 v[16:19], v[180:183], v[204:207], v[16:19]
	v_mfma_f32_16x16x32_bf16 v[4:7], v[148:151], v[212:215], v[4:7]
	v_mfma_f32_16x16x32_bf16 v[0:3], v[180:183], v[212:215], v[0:3]
	s_barrier
	s_add_i32 s31, s31, 2
	s_add_u32 s29, s29, 0x100
	s_addc_u32 s30, s30, 0
	s_cmp_gt_u32 s31, 41
	s_mov_b64 s[10:11], s[12:13]
	s_cbranch_scc0 .LBB0_264
	s_and_b64 vcc, exec, s[52:53]
	s_cbranch_vccz .LBB0_267
	s_barrier
